# v55 plus the leading group's loop-exit alignment barrier moved down into the straight-line start of each GEMM epilogue (for out-proj/down: behind its residual loads and their wait)
# baseline (speedup 1.0000x reference)
; #define LAS __attribute__((address_space(3)))
; #define PG8_BAR __builtin_amdgcn_s_barrier()
; #define EPI_ROWS(u) { const int _l = lane_id(); fr = _l & 15; fq = _l >> 4; } const int row0 = (u).pm * 256 + wr * 64 + fr
;     ...
;         if constexpr (ALIGN_EPI) { if (wr == 0) PG8_BAR; }
;     __device__ __forceinline__ void operator()(const f32x4 (&acc)[2][2][4][2], const pg8::Unit& u, int wr, int wc, int fr, int fq) const {
;         EPI_ROWS(u); const LAS float* rsl = (const LAS float*)(lds + EPI_RS + u.par * 1024) + wr * 64 + fr; const int sec = u.pn >> 3, c0 = (u.pn & 7) * 256 + wc * 32 + 8 * fq;
;         const float* lbs = (const float*)(ws + WS_LBS) + (layer >> 1) * 2048;
;         f32x4 lb[2][2] = {};
;         if (sec == 1) {
; #pragma unroll
;             for (int bj = 0; bj < 2; ++bj) { lb[bj][0] = *(const f32x4*)(lbs + c0 + bj * 128); lb[bj][1] = *(const f32x4*)(lbs + c0 + bj * 128 + 4); }
;             asm volatile("" ::: "memory"); }
.LBB0_203:
	s_lshl_b32 s3, s6, 8
	s_and_b32 s3, s3, 0x700
	v_mbcnt_lo_u32_b32 v146, -1, 0
	v_mbcnt_hi_u32_b32 v146, -1, v146
	s_ashr_i32 s2, s6, 3
	v_ashrrev_i32_e32 v26, 1, v146
	s_or_b32 s3, s3, s48
	v_and_b32_e32 v26, -8, v26
	s_cmp_lg_u32 s2, 1
	v_add_u32_e32 v164, s3, v26
	s_cselect_b64 s[30:31], -1, 0
	v_mov_b32_e32 v42, 0
	s_and_b64 vcc, exec, s[30:31]
	v_ashrrev_i32_e32 v165, 31, v164
	v_mov_b32_e32 v43, 0
	v_mov_b32_e32 v44, 0
	v_mov_b32_e32 v45, 0
	v_mov_b32_e32 v46, 0
	v_mov_b32_e32 v47, 0
	v_mov_b32_e32 v48, 0
	v_mov_b32_e32 v49, 0
	v_mov_b32_e32 v26, 0
	v_mov_b32_e32 v27, 0
	v_mov_b32_e32 v28, 0
	v_mov_b32_e32 v29, 0
	v_mov_b32_e32 v30, 0
	v_mov_b32_e32 v31, 0
	v_mov_b32_e32 v32, 0
	v_mov_b32_e32 v33, 0
	s_cselect_b32 s100, 1, 0
	s_cmp_eq_u64 s[14:15], 0
	s_cbranch_scc1 .Lxb_ic
	s_barrier
.Lxb_ic:
	s_cmp_lg_u32 s100, 0
	s_cbranch_vccnz .LBB0_205
	v_lshl_add_u64 v[30:31], v[164:165], 2, s[16:17]
	global_load_dwordx4 v[42:45], v[30:31], off
	global_load_dwordx4 v[46:49], v[30:31], off offset:16
	global_load_dwordx4 v[26:29], v[30:31], off offset:512
	s_nop 0
	global_load_dwordx4 v[30:33], v[30:31], off offset:528

; #define LAS __attribute__((address_space(3)))
; __device__ __forceinline__ unsigned cvt_pk_bf16(float lo, float hi) { const f32x2 v = {lo, hi}; unsigned r = __builtin_bit_cast(unsigned, __builtin_convertvector(v, bf16x2_t)); asm volatile("" : "+v"(r)); return r; }
; #define PG8_BAR __builtin_amdgcn_s_barrier()
;     ...
;         if constexpr (ALIGN_EPI) { if (wr == 0) PG8_BAR; }
;     __device__ __forceinline__ void operator()(const f32x4 (&acc)[2][2][4][2], const pg8::Unit& u, int wr, int wc, int fr, int fq) const {
;         EPI_ROWS(u); const int pn = u.pn, cb = wc * 32 + 4 * fq;
;         const LAS float* rsl = (const LAS float*)(lds + EPI_RS + u.par * 1024) + wr * 64 + fr; float* ssqq = (float*)(ws + WS_SSQQ) + (size_t)(li * 8 + (pn & 1) * 4 + wc) * MT; float* ssqkv = (float*)(ws + WS_SSQKV) + (size_t)(li * 8 + (pn & 1) * 4 + wc) * MT;
;         bf16_t* cqb = (bf16_t*)(ws + WS_CQB); bf16_t* zb = (bf16_t*)(ws + WS_ZB);
; #pragma unroll
;         for (int ai = 0; ai < 2; ++ai)
; #pragma unroll
;             for (int m = 0; m < 4; ++m) {
;                 const int r = EPI_ROW(ai, m); const float rs = rsl[ai * 128 + m * 16];
;                 f32x4 v[2][2]; float sq = 0.f;
; #pragma unroll
;                 for (int bj = 0; bj < 2; ++bj)
; #pragma unroll
;                     for (int n = 0; n < 2; ++n) { v[bj][n] = acc[ai][bj][m][n] * rs; sq += (v[bj][n][0] * v[bj][n][0] + v[bj][n][1] * v[bj][n][1]) + (v[bj][n][2] * v[bj][n][2] + v[bj][n][3] * v[bj][n][3]); }
;                 if (pn < 2) {
;                     bf16_t* o = cqb + (size_t)r * QR + pn * 256 + cb;
; #pragma unroll
;                     for (int bj = 0; bj < 2; ++bj)
; #pragma unroll
;                         for (int n = 0; n < 2; ++n) { u32x2 w; w.x = cvt_pk_bf16(v[bj][n][0], v[bj][n][1]); w.y = cvt_pk_bf16(v[bj][n][2], v[bj][n][3]); *(u32x2*)(o + bj * 128 + n * 16) = w; }
;                     sq = row4_sum(sq); if (fq == 0) ssqq[r] = sq;
;                 } else if (pn < 4) {
;                     float* o = (r < MP ? out + O_LATP + ((size_t)li * MP + r) * KVR : out + O_LATS + ((size_t)li * MS + (r - MP)) * KVR) + (pn - 2) * 256 + cb;
; #pragma unroll
;                     for (int bj = 0; bj < 2; ++bj)
; #pragma unroll
;                         for (int n = 0; n < 2; ++n) *(f32x4*)(o + bj * 128 + n * 16) = v[bj][n];
;                     sq = row4_sum(sq); if (fq == 0) ssqkv[r] = sq;
.LBB0_706:
	v_mbcnt_lo_u32_b32 v0, -1, 0
	v_mbcnt_hi_u32_b32 v0, -1, v0
	v_readlane_b32 s2, v255, 32
	v_ashrrev_i32_e32 v138, 2, v0
	v_and_b32_e32 v138, -4, v138
	v_add_u32_e32 v140, s2, v138
	s_lshl_b32 s2, s7, 10
	v_and_b32_e32 v148, 15, v0
	s_add_i32 s2, s80, s2
	v_lshl_add_u32 v149, v148, 2, s2
	s_lshl_b32 s2, s6, 2
	s_and_b32 s2, s2, 4
	s_or_b32 s2, s2, s22
	s_mul_i32 s60, s2, 0x4800
	s_lshl_b64 s[2:3], s[60:61], 2
	s_add_u32 s36, s89, s2
	s_addc_u32 s37, s91, s3
	s_add_u32 s38, s92, s2
	s_addc_u32 s39, s93, s3
	s_cmp_gt_i32 s6, 1
	s_cselect_b64 s[10:11], -1, 0
	s_cmp_gt_u32 s6, 3
	s_cselect_b64 s[44:45], -1, 0
	s_cmp_gt_u32 s6, 7
	s_cselect_b64 s[42:43], -1, 0
	s_lshl_b32 s40, s6, 8
	v_cmp_gt_u32_e64 s[6:7], 16, v0
	ds_read_b32 v0, v149
	s_add_i32 s60, s40, 0xfffffc00
	s_lshl_b64 s[2:3], s[60:61], 1
	v_ashrrev_i32_e32 v141, 31, v140
	s_add_u32 s2, s96, s2
	s_waitcnt lgkmcnt(0)
	v_pk_mul_f32 v[128:129], v[128:129], v[0:1] op_sel_hi:[1,0]
	v_pk_mul_f32 v[126:127], v[126:127], v[0:1] op_sel_hi:[1,0]
	v_mul_f32_e32 v151, v129, v129
	v_mul_f32_e32 v139, v127, v127
	v_fmac_f32_e32 v139, v126, v126
	v_fmac_f32_e32 v151, v128, v128
	v_pk_mul_f32 v[124:125], v[124:125], v[0:1] op_sel_hi:[1,0]
	v_pk_mul_f32 v[122:123], v[122:123], v[0:1] op_sel_hi:[1,0]
	v_add_f32_e32 v139, v139, v151
	v_mul_f32_e32 v151, v123, v123
	v_mul_f32_e32 v152, v125, v125
	v_fmac_f32_e32 v151, v122, v122
	v_fmac_f32_e32 v152, v124, v124
	v_add_f32_e32 v151, v151, v152
	v_pk_mul_f32 v[120:121], v[120:121], v[0:1] op_sel_hi:[1,0]
	v_pk_mul_f32 v[118:119], v[118:119], v[0:1] op_sel_hi:[1,0]
	v_add_f32_e32 v139, v139, v151
	v_mul_f32_e32 v151, v119, v119
	v_mul_f32_e32 v152, v121, v121
	v_fmac_f32_e32 v151, v118, v118
	v_fmac_f32_e32 v152, v120, v120
	v_add_f32_e32 v151, v151, v152
	v_pk_mul_f32 v[116:117], v[116:117], v[0:1] op_sel_hi:[1,0]
	v_pk_mul_f32 v[114:115], v[114:115], v[0:1] op_sel_hi:[1,0]
	s_addc_u32 s3, s97, s3
	v_lshlrev_b64 v[144:145], 1, v[140:141]
	s_ashr_i32 s41, s40, 31
	v_add_f32_e32 v139, v151, v139
	v_mul_f32_e32 v0, v115, v115
	v_mul_f32_e32 v151, v117, v117
	v_or_b32_e32 v138, s46, v148
	v_lshl_add_u64 v[142:143], s[2:3], 0, v[144:145]
	s_lshl_b64 s[2:3], s[40:41], 1
	v_fmac_f32_e32 v0, v114, v114
	v_fmac_f32_e32 v151, v116, v116
	v_lshl_add_u32 v138, s8, 8, v138
	s_add_u32 s12, s94, s2
	v_add_f32_e32 v0, v0, v151
	v_cmp_gt_i32_e64 s[8:9], 64, v140
	s_mov_b32 s60, s40
	s_addc_u32 s13, s95, s3
	v_add_u32_e32 v150, 0xffffc000, v138
	v_add_f32_e32 v151, v0, v139
	s_mov_b64 s[2:3], -1
	s_and_b64 vcc, exec, s[10:11]
	s_cselect_b32 s100, 1, 0
	s_cmp_eq_u64 s[18:19], 0
	s_cbranch_scc1 .Lxb_ia
	s_barrier
.Lxb_ia:
	s_cmp_lg_u32 s100, 0
	s_cbranch_vccz .LBB0_720
	s_and_b64 vcc, exec, s[44:45]
	s_cbranch_vccz .LBB0_715
	s_and_b64 vcc, exec, s[42:43]
	s_cbranch_vccz .LBB0_712
	s_and_saveexec_b64 s[2:3], s[8:9]
	s_cbranch_execz .LBB0_711
	s_movk_i32 s27, 0x4000
	v_cmp_gt_i32_e32 vcc, s27, v138
	v_mov_b32_e32 v0, 0xf3b0000
	v_mov_b32_e32 v139, 0xd000000
	v_cndmask_b32_e32 v0, v0, v139, vcc
	v_readlane_b32 s24, v255, 20
	v_lshl_add_u64 v[152:153], s[0:1], 0, v[0:1]
	v_cndmask_b32_e64 v0, 19, 22, vcc
	v_readlane_b32 s25, v255, 21
	s_nop 1
	v_lshlrev_b64 v[154:155], v0, s[24:25]
	v_ashrrev_i32_e32 v0, 31, v138
	v_lshl_add_u64 v[152:153], v[152:153], 0, v[154:155]
	v_cndmask_b32_e32 v155, 0, v0, vcc
	v_cndmask_b32_e32 v154, v150, v138, vcc
	v_lshlrev_b64 v[154:155], 8, v[154:155]
	v_lshl_add_u64 v[152:153], v[152:153], 0, v[154:155]
	v_lshl_add_u64 v[152:153], v[140:141], 2, v[152:153]
	global_store_dwordx4 v[152:153], v[126:129], off
	global_store_dwordx4 v[152:153], v[122:125], off offset:64

; #define LAS __attribute__((address_space(3)))
; #define PG8_BAR __builtin_amdgcn_s_barrier()
; #define EPI_ROWS(u) { const int _l = lane_id(); fr = _l & 15; fq = _l >> 4; } const int row0 = (u).pm * 256 + wr * 64 + fr
; #define EPIQ_ROPE(dst, ai_, m_) do { const int rr_ = rope_row(EPI_ROW(ai_, m_)); _Pragma("unroll") for (int bj = 0; bj < 2; ++bj) if (cc[bj] >= NOPE) { \
;             const size_t ix_ = ((size_t)rr_ * 32 + ((cc[bj] - NOPE) >> 1)) >> 1; dst[bj][0] = rope[ix_]; dst[bj][1] = rope[ix_ + 1]; } } while (0)
;     ...
;         if constexpr (ALIGN_EPI) { if (wr == 0) PG8_BAR; }
;     __device__ __forceinline__ void operator()(const f32x4 (&acc)[2][2][4][2], const pg8::Unit& u, int wr, int wc, int fr, int fq) const {
;         EPI_ROWS(u); const LAS float* sql = (const LAS float*)(lds + EPI_LDS + u.par * 8192) + wr * 64 + fr; const f32x4* rope = (const f32x4*)(ws + WS_ROPE);
;         bf16_t* qp = (bf16_t*)(ws + WS_QP); bf16_t* qns = (bf16_t*)(ws + WS_QNS); bf16_t* qs = (bf16_t*)(ws + WS_QS);
;         int hh[2], cc[2];
; #pragma unroll
;         for (int bj = 0; bj < 2; ++bj) { const int c = u.pn * 256 + bj * 128 + wc * 32 + 8 * fq; hh[bj] = c / QKD; cc[bj] = c - hh[bj] * QKD; }
;         f32x4 T[2][2] = {}, Tn[2][2] = {};
;     ...
;         EPIQ_ROPE(T, 0, 0);
.LBB0_1195:
	v_mbcnt_lo_u32_b32 v0, -1, 0
	v_mbcnt_hi_u32_b32 v0, -1, v0
	s_lshl_b32 s2, s6, 8
	v_ashrrev_i32_e32 v10, 1, v0
	v_and_b32_e32 v10, -8, v10
	s_or_b32 s2, s2, s41
	v_add_u32_e32 v10, s2, v10
	v_mul_hi_i32 v11, v10, s82
	v_lshrrev_b32_e32 v12, 31, v11
	v_ashrrev_i32_e32 v11, 5, v11
	v_add_u32_e32 v208, v11, v12
	s_movk_i32 s2, 0xff40
	s_add_i32 s7, s8, s46
	v_mad_u64_u32 v[202:203], s[2:3], v208, s2, v[10:11]
	v_and_b32_e32 v199, 15, v0
	v_or_b32_e32 v210, s7, v199
	s_movk_i32 s2, 0x3fff
	v_cmp_lt_i32_e64 s[12:13], s2, v210
	v_mov_b32_e32 v0, s7
	s_movk_i32 s2, 0x7cf
	v_bitop3_b32 v0, v199, s2, v0 bitop3:0xc8
	s_movk_i32 s2, 0x4000
	v_or_b32_e32 v221, 0x800, v199
	v_cmp_gt_i32_e32 vcc, s2, v210
	v_cmp_lt_i32_e64 s[8:9], s65, v202
	v_mov_b32_e32 v182, 0
	v_cndmask_b32_e32 v0, v221, v0, vcc
	v_lshlrev_b32_e32 v11, 5, v0
	v_add_u32_e32 v0, 0xffffff80, v202
	v_lshrrev_b32_e32 v218, 1, v0
	v_mov_b32_e32 v183, 0
	v_mov_b32_e32 v184, 0
	v_mov_b32_e32 v185, 0
	v_mov_b32_e32 v178, 0
	v_mov_b32_e32 v179, 0
	v_mov_b32_e32 v180, 0
	v_mov_b32_e32 v181, 0
	s_cselect_b32 s100, 1, 0
	s_cmp_eq_u64 s[16:17], 0
	s_cbranch_scc1 .Lxb_q
	s_barrier
.Lxb_q:
	s_cmp_lg_u32 s100, 0
	s_and_saveexec_b64 s[2:3], s[8:9]
	s_cbranch_execz .LBB0_1197
	v_add_u32_e32 v0, v218, v11
	v_lshrrev_b32_e32 v0, 1, v0
	v_lshl_add_u64 v[12:13], v[0:1], 4, s[20:21]
	global_load_dwordx4 v[182:185], v[12:13], off
	global_load_dwordx4 v[178:181], v[12:13], off offset:16

; #define PG8_BAR __builtin_amdgcn_s_barrier()
; #define EPI_ROWS(u) { const int _l = lane_id(); fr = _l & 15; fq = _l >> 4; } const int row0 = (u).pm * 256 + wr * 64 + fr
; __device__ __forceinline__ u32x4 pack8(const f32x4 a, const f32x4 b) { u32x4 w; w.x = cvt_pk_bf16(a[0], a[1]); w.y = cvt_pk_bf16(a[2], a[3]); w.z = cvt_pk_bf16(b[0], b[1]); w.w = cvt_pk_bf16(b[2], b[3]); return w; }
;     ...
;         if constexpr (ALIGN_EPI) { if (wr == 0) PG8_BAR; }
;     __device__ __forceinline__ void operator()(const f32x4 (&acc)[2][2][4][2], const pg8::Unit& u, int wr, int wc, int fr, int fq) const {
;         EPI_ROWS(u); const int cl = wc * 32 + 8 * fq;
; #pragma unroll
;         for (int bj = 0; bj < 2; ++bj) {
;             bf16_t* base; size_t ldc;
;             if (MODE == 0) { if (u.pn < 4) { base = (bf16_t*)(ws + WS_KP) + (2 * u.pn + bj) * QKD; ldc = HEADS * QKD; } else { base = (bf16_t*)(ws + WS_VP) + (u.pn - 4) * 256 + bj * 128; ldc = HEADS * VD; } }
;             else if (MODE == 1) { base = (bf16_t*)(ws + WS_QS) + (u.pn >> 1) * KVW + (u.pn & 1) * 256 + bj * 128; ldc = HEADS * KVW; }
;             else if (MODE == 2) { base = (bf16_t*)(ws + WS_YCAT) + 1024 + u.pn * 256 + bj * 128; ldc = DM; }
;             else { base = (bf16_t*)(ws + WS_YCAT) + (size_t)MP * DM + u.pn * 256 + bj * 128; ldc = DM; }
; #pragma unroll
;             for (int ai = 0; ai < 2; ++ai)
; #pragma unroll
;                 for (int m = 0; m < 4; ++m) *(u32x4*)(base + (size_t)EPI_ROW(ai, m) * ldc + cl) = pack8(acc[ai][bj][m][0], acc[ai][bj][m][1]);
.LBB0_1457:
	s_cmp_gt_i32 s72, 3
	s_cselect_b64 s[6:7], -1, 0
	s_lshl_b32 s2, s72, 8
	s_add_i32 s60, s2, 0xfffffc00
	s_mov_b64 s[20:21], -1
	s_and_b64 vcc, exec, s[6:7]
	v_mbcnt_lo_u32_b32 v140, -1, 0
	v_mbcnt_hi_u32_b32 v140, -1, v140
	s_cselect_b32 s100, 1, 0
	s_cmp_eq_u64 s[12:13], 0
	s_cbranch_scc1 .Lxb_kv
	s_barrier
.Lxb_kv:
	s_cmp_lg_u32 s100, 0
	s_cbranch_vccz .LBB0_1459
	s_lshl_b64 s[2:3], s[60:61], 1
	s_add_u32 s2, s62, s2
	s_addc_u32 s3, s63, s3
	s_mov_b64 s[20:21], 0

; __device__ __forceinline__ float bf_lo(unsigned w) { return __uint_as_float(w << 16); }
; __device__ __forceinline__ float bf_hi(unsigned w) { return __uint_as_float(w & 0xffff0000u); }
; __device__ __forceinline__ int lane_id() { int l; asm volatile("v_mbcnt_lo_u32_b32 %0, -1, 0\n\tv_mbcnt_hi_u32_b32 %0, -1, %0" : "=v"(l)); return l; }
; #define PG8_BAR __builtin_amdgcn_s_barrier()
;     ...
;         if constexpr (ALIGN_EPI) { if (wr == 0) PG8_BAR; }
;     __device__ __forceinline__ void operator()(const f32x4 (&acc)[2][2][NM][2], const pg8::Unit& u, int wr, int wc, int fr, int fq) const {
;         { const int _l = lane_id(); fr = _l & 15; fq = _l >> 4; } const int row0 = u.pm * (64 * NM) + wr * (16 * NM) + fr;
;         const int c0 = u.pn * 256 + wc * 32 + 8 * fq; bf16_t* XB = (bf16_t*)(ws + WS_XB); float* ssq = (float*)(ws + WS_SSQP) + (size_t)(nidx * 32 + u.pn * 4 + wc) * MT;
;         u32x4 q[2][NM][2];
;         if (!first) {
; #pragma unroll
;             for (int ai = 0; ai < 2; ++ai)
; #pragma unroll
;                 for (int m = 0; m < NM; ++m)
; #pragma unroll
;                     for (int bj = 0; bj < 2; ++bj) q[ai][m][bj] = *(const u32x4*)(XB + (size_t)(row0 + ai * (32 * NM) + m * 16) * DM + c0 + bj * 128);
;             asm volatile("" ::: "memory");
;         }
;         float sqv[2][NM];
; #pragma unroll
;         for (int ai = 0; ai < 2; ++ai)
; #pragma unroll
;             for (int m = 0; m < NM; ++m) {
;                 const int r = row0 + ai * (32 * NM) + m * 16; float sq = 0.f;
; #pragma unroll
;                 for (int bj = 0; bj < 2; ++bj) { const int c = c0 + bj * 128; f32x4 a, b;
;                     if (first) { const float* xo = (r < MP ? xp + (size_t)r * DM : xs + (size_t)(r - MP) * DM) + c; a = *(const f32x4*)xo; b = *(const f32x4*)(xo + 4); }
;                     else { const u32x4 w = q[ai][m][bj]; a = (f32x4){bf_lo(w.x), bf_hi(w.x), bf_lo(w.y), bf_hi(w.y)}; b = (f32x4){bf_lo(w.z), bf_hi(w.z), bf_lo(w.w), bf_hi(w.w)}; }
;                     a = a + acc[ai][bj][m][0]; b = b + acc[ai][bj][m][1];
;                     *(u32x4*)(XB + (size_t)r * DM + c) = pack8(a, b);
;                     sq += ((a[0] * a[0] + a[1] * a[1]) + (a[2] * a[2] + a[3] * a[3])) + ((b[0] * b[0] + b[1] * b[1]) + (b[2] * b[2] + b[3] * b[3])); }
.LBB0_1653:
	s_mul_i32 s2, s57, 0xc0
	s_add_i32 s2, s2, s39
	v_mbcnt_lo_u32_b32 v168, -1, 0
	v_mbcnt_hi_u32_b32 v168, -1, v168
	v_readlane_b32 s3, v255, 32
	v_and_or_b32 v152, v168, 15, s2
	s_lshl_b32 s2, s20, 8
	v_ashrrev_i32_e32 v90, 1, v168
	s_or_b32 s2, s2, s3
	v_and_b32_e32 v90, -8, v90
	v_add_u32_e32 v90, s2, v90
	v_ashrrev_i32_e32 v91, 31, v90
	v_lshlrev_b64 v[154:155], 1, v[90:91]
	v_ashrrev_i32_e32 v153, 31, v152
	v_lshl_add_u64 v[90:91], s[12:13], 0, v[154:155]
	v_lshlrev_b64 v[174:175], 12, v[152:153]
	v_lshl_add_u64 v[92:93], v[90:91], 0, v[174:175]
	global_load_dwordx4 v[170:173], v[92:93], off
	global_load_dwordx4 v[138:141], v[92:93], off offset:256
	s_lshl_b32 s2, s20, 2
	s_add_i32 s2, s2, s52
	s_mul_hi_i32 s3, s2, 0x12000
	s_mul_i32 s2, s2, 0x12000
	s_add_u32 s8, s50, s2
	s_addc_u32 s9, s51, s3
	s_mov_b64 s[2:3], 0x10000
	v_lshl_add_u64 v[164:165], v[174:175], 0, s[2:3]
	v_lshl_add_u64 v[92:93], v[90:91], 0, v[164:165]
	global_load_dwordx4 v[134:137], v[92:93], off
	global_load_dwordx4 v[130:133], v[92:93], off offset:256
	v_lshl_add_u64 v[162:163], v[174:175], 0, s[76:77]
	v_lshl_add_u64 v[92:93], v[90:91], 0, v[162:163]
	global_load_dwordx4 v[126:129], v[92:93], off
	global_load_dwordx4 v[122:125], v[92:93], off offset:256
	s_mov_b64 s[2:3], 0x60000
	v_lshl_add_u64 v[160:161], v[174:175], 0, s[2:3]
	v_lshl_add_u64 v[92:93], v[90:91], 0, v[160:161]
	global_load_dwordx4 v[118:121], v[92:93], off
	global_load_dwordx4 v[114:117], v[92:93], off offset:256
	s_mov_b64 s[2:3], 0x70000
	v_lshl_add_u64 v[158:159], v[174:175], 0, s[2:3]
	v_lshl_add_u64 v[92:93], v[90:91], 0, v[158:159]
	global_load_dwordx4 v[102:105], v[92:93], off
	global_load_dwordx4 v[98:101], v[92:93], off offset:256
	s_mov_b64 s[2:3], 0x80000
	v_lshl_add_u64 v[156:157], v[174:175], 0, s[2:3]
	v_lshl_add_u64 v[90:91], v[90:91], 0, v[156:157]
	global_load_dwordx4 v[94:97], v[90:91], off
	s_nop 0
	global_load_dwordx4 v[90:93], v[90:91], off offset:256
	v_lshl_add_u64 v[174:175], s[12:13], 0, v[174:175]
	v_cmp_gt_u32_e32 vcc, 16, v168
	s_waitcnt vmcnt(0)
	s_cselect_b32 s100, 1, 0
	s_cmp_eq_u64 s[10:11], 0
	s_cbranch_scc1 .Lxb_op
	s_barrier
.Lxb_op:
	s_cmp_lg_u32 s100, 0
	v_lshlrev_b32_e32 v176, 16, v170
	v_and_b32_e32 v177, 0xffff0000, v170
	v_lshlrev_b32_e32 v170, 16, v171
	v_and_b32_e32 v171, 0xffff0000, v171
	v_lshlrev_b32_e32 v178, 16, v172
	v_and_b32_e32 v179, 0xffff0000, v172
	v_lshlrev_b32_e32 v172, 16, v173
	v_and_b32_e32 v173, 0xffff0000, v173
	v_pk_add_f32 v[112:113], v[112:113], v[170:171]
	v_pk_add_f32 v[170:171], v[110:111], v[176:177]
	v_pk_add_f32 v[172:173], v[108:109], v[172:173]
	v_pk_add_f32 v[176:177], v[106:107], v[178:179]
	v_cvt_pk_bf16_f32 v108, v170, v171
	v_cvt_pk_bf16_f32 v109, v112, v113
	v_cvt_pk_bf16_f32 v110, v176, v177
	v_cvt_pk_bf16_f32 v111, v172, v173
	v_lshl_add_u64 v[106:107], v[174:175], 0, v[154:155]
	global_store_dwordx4 v[106:107], v[108:111], off
	s_nop 1
	v_mul_f32_e32 v108, v171, v171
	v_mul_f32_e32 v109, v113, v113
	v_fmac_f32_e32 v108, v170, v170
	v_fmac_f32_e32 v109, v112, v112
	v_add_f32_e32 v108, v108, v109
	v_mul_f32_e32 v109, v177, v177
	v_mul_f32_e32 v110, v173, v173
	v_fmac_f32_e32 v109, v176, v176
	v_fmac_f32_e32 v110, v172, v172
	v_add_f32_e32 v109, v109, v110
	v_add_f32_e32 v169, v108, v109
	v_lshlrev_b32_e32 v108, 16, v138
	v_and_b32_e32 v109, 0xffff0000, v138
	v_lshlrev_b32_e32 v110, 16, v139
	v_and_b32_e32 v111, 0xffff0000, v139
	v_lshlrev_b32_e32 v112, 16, v140
	v_and_b32_e32 v113, 0xffff0000, v140
	v_lshlrev_b32_e32 v138, 16, v141
	v_and_b32_e32 v139, 0xffff0000, v141
	v_pk_add_f32 v[88:89], v[88:89], v[110:111]
	v_pk_add_f32 v[86:87], v[86:87], v[108:109]
	v_pk_add_f32 v[108:109], v[84:85], v[138:139]
	v_pk_add_f32 v[110:111], v[82:83], v[112:113]
	v_cvt_pk_bf16_f32 v82, v86, v87
	v_cvt_pk_bf16_f32 v83, v88, v89
	v_cvt_pk_bf16_f32 v84, v110, v111
	v_cvt_pk_bf16_f32 v85, v108, v109
	global_store_dwordx4 v[106:107], v[82:85], off offset:256
	v_lshlrev_b32_e32 v106, 16, v137
	v_and_b32_e32 v107, 0xffff0000, v137
	v_mul_f32_e32 v82, v87, v87
	v_mul_f32_e32 v83, v89, v89
	v_fmac_f32_e32 v82, v86, v86
	v_fmac_f32_e32 v83, v88, v88
	v_add_f32_e32 v82, v82, v83
	v_mul_f32_e32 v83, v111, v111
	v_mul_f32_e32 v84, v109, v109
	v_fmac_f32_e32 v83, v110, v110
	v_fmac_f32_e32 v84, v108, v108
	v_add_f32_e32 v83, v83, v84
	v_add_f32_e32 v82, v82, v83
	v_add_f32_e32 v108, v169, v82
	v_lshlrev_b32_e32 v82, 16, v134
	v_and_b32_e32 v83, 0xffff0000, v134
	v_lshlrev_b32_e32 v84, 16, v135
	v_and_b32_e32 v85, 0xffff0000, v135
	v_lshlrev_b32_e32 v88, 16, v136
	v_and_b32_e32 v89, 0xffff0000, v136
	v_pk_add_f32 v[80:81], v[80:81], v[84:85]
	v_pk_add_f32 v[78:79], v[78:79], v[82:83]
	v_pk_add_f32 v[76:77], v[76:77], v[106:107]
	v_pk_add_f32 v[74:75], v[74:75], v[88:89]
	v_lshl_add_u64 v[86:87], s[12:13], 0, v[164:165]
	v_cvt_pk_bf16_f32 v82, v78, v79
	v_cvt_pk_bf16_f32 v83, v80, v81
	v_cvt_pk_bf16_f32 v84, v74, v75
	v_cvt_pk_bf16_f32 v85, v76, v77
	v_lshl_add_u64 v[86:87], v[86:87], 0, v[154:155]
	global_store_dwordx4 v[86:87], v[82:85], off
	v_lshlrev_b32_e32 v88, 16, v132
	v_and_b32_e32 v89, 0xffff0000, v132
	v_lshlrev_b32_e32 v82, 16, v130
	v_and_b32_e32 v83, 0xffff0000, v130
	v_lshlrev_b32_e32 v84, 16, v131
	v_and_b32_e32 v85, 0xffff0000, v131
	v_lshlrev_b32_e32 v106, 16, v133
	v_and_b32_e32 v107, 0xffff0000, v133
	v_pk_add_f32 v[72:73], v[72:73], v[84:85]
	v_pk_add_f32 v[70:71], v[70:71], v[82:83]
	v_pk_add_f32 v[68:69], v[68:69], v[106:107]
	v_pk_add_f32 v[66:67], v[66:67], v[88:89]
	v_cvt_pk_bf16_f32 v82, v70, v71
	v_cvt_pk_bf16_f32 v83, v72, v73
	v_cvt_pk_bf16_f32 v84, v66, v67
	v_cvt_pk_bf16_f32 v85, v68, v69
; __device__ __forceinline__ float bf_lo(unsigned w) { return __uint_as_float(w << 16); }
; __device__ __forceinline__ float bf_hi(unsigned w) { return __uint_as_float(w & 0xffff0000u); }
; __device__ __forceinline__ u32x4 pack8(const f32x4 a, const f32x4 b) { u32x4 w; w.x = cvt_pk_bf16(a[0], a[1]); w.y = cvt_pk_bf16(a[2], a[3]); w.z = cvt_pk_bf16(b[0], b[1]); w.w = cvt_pk_bf16(b[2], b[3]); return w; }
;     __device__ __forceinline__ void operator()(const f32x4 (&acc)[2][2][NM][2], const pg8::Unit& u, int wr, int wc, int fr, int fq) const {
;     ...
;                 const int r = row0 + ai * (32 * NM) + m * 16; float sq = 0.f;
; #pragma unroll
;                 for (int bj = 0; bj < 2; ++bj) { const int c = c0 + bj * 128; f32x4 a, b;
;                     if (first) { const float* xo = (r < MP ? xp + (size_t)r * DM : xs + (size_t)(r - MP) * DM) + c; a = *(const f32x4*)xo; b = *(const f32x4*)(xo + 4); }
;                     else { const u32x4 w = q[ai][m][bj]; a = (f32x4){bf_lo(w.x), bf_hi(w.x), bf_lo(w.y), bf_hi(w.y)}; b = (f32x4){bf_lo(w.z), bf_hi(w.z), bf_lo(w.w), bf_hi(w.w)}; }
;                     a = a + acc[ai][bj][m][0]; b = b + acc[ai][bj][m][1];
;                     *(u32x4*)(XB + (size_t)r * DM + c) = pack8(a, b);
;                     sq += ((a[0] * a[0] + a[1] * a[1]) + (a[2] * a[2] + a[3] * a[3])) + ((b[0] * b[0] + b[1] * b[1]) + (b[2] * b[2] + b[3] * b[3])); }
;                 sqv[ai][m] = sq;
;             }
; #pragma unroll
;         for (int ai = 0; ai < 2; ++ai)
; #pragma unroll
;             for (int m = 0; m < NM; ++m) { const float sq = row4_sum(sqv[ai][m]); if (fq == 0) ssq[row0 + ai * (32 * NM) + m * 16] = sq; }
	global_store_dwordx4 v[86:87], v[82:85], off offset:256
	v_lshlrev_b32_e32 v88, 16, v128
	v_and_b32_e32 v89, 0xffff0000, v128
	v_lshlrev_b32_e32 v82, 16, v126
	v_and_b32_e32 v83, 0xffff0000, v126
	v_lshlrev_b32_e32 v84, 16, v127
	v_and_b32_e32 v85, 0xffff0000, v127
	v_lshlrev_b32_e32 v106, 16, v129
	v_and_b32_e32 v107, 0xffff0000, v129
	v_pk_add_f32 v[64:65], v[64:65], v[84:85]
	v_pk_add_f32 v[62:63], v[62:63], v[82:83]
	v_pk_add_f32 v[60:61], v[60:61], v[106:107]
	v_pk_add_f32 v[58:59], v[58:59], v[88:89]
	v_lshl_add_u64 v[86:87], s[12:13], 0, v[162:163]
	v_cvt_pk_bf16_f32 v82, v62, v63
	v_cvt_pk_bf16_f32 v83, v64, v65
	v_cvt_pk_bf16_f32 v84, v58, v59
	v_cvt_pk_bf16_f32 v85, v60, v61
	v_lshl_add_u64 v[86:87], v[86:87], 0, v[154:155]
	global_store_dwordx4 v[86:87], v[82:85], off
	v_lshlrev_b32_e32 v88, 16, v124
	v_and_b32_e32 v89, 0xffff0000, v124
	v_lshlrev_b32_e32 v82, 16, v122
	v_and_b32_e32 v83, 0xffff0000, v122
	v_lshlrev_b32_e32 v84, 16, v123
	v_and_b32_e32 v85, 0xffff0000, v123
	v_lshlrev_b32_e32 v106, 16, v125
	v_and_b32_e32 v107, 0xffff0000, v125
	v_pk_add_f32 v[56:57], v[56:57], v[84:85]
	v_pk_add_f32 v[54:55], v[54:55], v[82:83]
	v_pk_add_f32 v[52:53], v[52:53], v[106:107]
	v_pk_add_f32 v[50:51], v[50:51], v[88:89]
	v_cvt_pk_bf16_f32 v82, v54, v55
	v_cvt_pk_bf16_f32 v83, v56, v57
	v_cvt_pk_bf16_f32 v84, v50, v51
	v_cvt_pk_bf16_f32 v85, v52, v53
	global_store_dwordx4 v[86:87], v[82:85], off offset:256
	v_lshlrev_b32_e32 v88, 16, v120
	v_and_b32_e32 v89, 0xffff0000, v120
	v_lshlrev_b32_e32 v82, 16, v118
	v_and_b32_e32 v83, 0xffff0000, v118
	v_lshlrev_b32_e32 v84, 16, v119
	v_and_b32_e32 v85, 0xffff0000, v119
	v_lshlrev_b32_e32 v106, 16, v121
	v_and_b32_e32 v107, 0xffff0000, v121
	v_pk_add_f32 v[48:49], v[48:49], v[84:85]
	v_pk_add_f32 v[46:47], v[46:47], v[82:83]
	v_pk_add_f32 v[44:45], v[44:45], v[106:107]
	v_pk_add_f32 v[42:43], v[42:43], v[88:89]
	v_lshl_add_u64 v[86:87], s[12:13], 0, v[160:161]
	v_cvt_pk_bf16_f32 v82, v46, v47
	v_cvt_pk_bf16_f32 v83, v48, v49
	v_cvt_pk_bf16_f32 v84, v42, v43
	v_cvt_pk_bf16_f32 v85, v44, v45
	v_lshl_add_u64 v[86:87], v[86:87], 0, v[154:155]
	global_store_dwordx4 v[86:87], v[82:85], off
	v_lshlrev_b32_e32 v88, 16, v116
	v_and_b32_e32 v89, 0xffff0000, v116
	v_lshlrev_b32_e32 v82, 16, v114
	v_and_b32_e32 v83, 0xffff0000, v114
	v_lshlrev_b32_e32 v84, 16, v115
	v_and_b32_e32 v85, 0xffff0000, v115
	v_lshlrev_b32_e32 v106, 16, v117
	v_and_b32_e32 v107, 0xffff0000, v117
	v_pk_add_f32 v[40:41], v[40:41], v[84:85]
	v_pk_add_f32 v[38:39], v[38:39], v[82:83]
	v_pk_add_f32 v[36:37], v[36:37], v[106:107]
	v_pk_add_f32 v[34:35], v[34:35], v[88:89]
	v_cvt_pk_bf16_f32 v82, v38, v39
	v_cvt_pk_bf16_f32 v83, v40, v41
	v_cvt_pk_bf16_f32 v84, v34, v35
	v_cvt_pk_bf16_f32 v85, v36, v37
	global_store_dwordx4 v[86:87], v[82:85], off offset:256
	v_lshlrev_b32_e32 v88, 16, v104
	v_and_b32_e32 v89, 0xffff0000, v104
	v_lshlrev_b32_e32 v82, 16, v102
	v_and_b32_e32 v83, 0xffff0000, v102
	v_lshlrev_b32_e32 v84, 16, v103
	v_and_b32_e32 v85, 0xffff0000, v103
	v_lshlrev_b32_e32 v102, 16, v105
	v_and_b32_e32 v103, 0xffff0000, v105
	v_pk_add_f32 v[32:33], v[32:33], v[84:85]
	v_pk_add_f32 v[30:31], v[30:31], v[82:83]
	v_pk_add_f32 v[28:29], v[28:29], v[102:103]
	v_pk_add_f32 v[26:27], v[26:27], v[88:89]
	v_lshl_add_u64 v[86:87], s[12:13], 0, v[158:159]
	v_cvt_pk_bf16_f32 v82, v30, v31
	v_cvt_pk_bf16_f32 v83, v32, v33
	v_cvt_pk_bf16_f32 v84, v26, v27
	v_cvt_pk_bf16_f32 v85, v28, v29
	v_lshl_add_u64 v[86:87], v[86:87], 0, v[154:155]
	global_store_dwordx4 v[86:87], v[82:85], off
	v_lshlrev_b32_e32 v88, 16, v100
	v_and_b32_e32 v89, 0xffff0000, v100
	v_lshlrev_b32_e32 v82, 16, v98
	v_and_b32_e32 v83, 0xffff0000, v98
	v_lshlrev_b32_e32 v84, 16, v99
	v_and_b32_e32 v85, 0xffff0000, v99
	v_lshlrev_b32_e32 v98, 16, v101
	v_and_b32_e32 v99, 0xffff0000, v101
	v_pk_add_f32 v[24:25], v[24:25], v[84:85]
	v_pk_add_f32 v[22:23], v[22:23], v[82:83]
	v_pk_add_f32 v[20:21], v[20:21], v[98:99]
	v_pk_add_f32 v[18:19], v[18:19], v[88:89]
	v_cvt_pk_bf16_f32 v82, v22, v23
	v_cvt_pk_bf16_f32 v83, v24, v25
	v_cvt_pk_bf16_f32 v84, v18, v19
	v_cvt_pk_bf16_f32 v85, v20, v21
	global_store_dwordx4 v[86:87], v[82:85], off offset:256
	v_lshlrev_b32_e32 v88, 16, v96
	v_and_b32_e32 v89, 0xffff0000, v96
	v_lshlrev_b32_e32 v82, 16, v94
	v_and_b32_e32 v83, 0xffff0000, v94
	v_lshlrev_b32_e32 v84, 16, v95
	v_and_b32_e32 v85, 0xffff0000, v95
	v_lshlrev_b32_e32 v94, 16, v97
	v_and_b32_e32 v95, 0xffff0000, v97
	v_pk_add_f32 v[16:17], v[16:17], v[84:85]
	v_pk_add_f32 v[14:15], v[14:15], v[82:83]
	v_lshl_add_u64 v[86:87], s[12:13], 0, v[156:157]
	v_pk_add_f32 v[12:13], v[12:13], v[94:95]
	v_pk_add_f32 v[10:11], v[10:11], v[88:89]
	v_cvt_pk_bf16_f32 v82, v14, v15
	v_cvt_pk_bf16_f32 v83, v16, v17
	v_cvt_pk_bf16_f32 v84, v10, v11
	v_cvt_pk_bf16_f32 v85, v12, v13
	v_lshl_add_u64 v[86:87], v[86:87], 0, v[154:155]
	global_store_dwordx4 v[86:87], v[82:85], off
	v_lshlrev_b32_e32 v88, 16, v92
	v_and_b32_e32 v89, 0xffff0000, v92
	v_lshlrev_b32_e32 v82, 16, v90
	v_and_b32_e32 v83, 0xffff0000, v90
	v_lshlrev_b32_e32 v84, 16, v91
	v_and_b32_e32 v85, 0xffff0000, v91
	v_lshlrev_b32_e32 v90, 16, v93
	v_and_b32_e32 v91, 0xffff0000, v93
	v_pk_add_f32 v[6:7], v[6:7], v[82:83]
	v_pk_add_f32 v[8:9], v[8:9], v[84:85]
	v_pk_add_f32 v[4:5], v[4:5], v[90:91]
	v_pk_add_f32 v[2:3], v[2:3], v[88:89]
	v_cvt_pk_bf16_f32 v82, v6, v7
	v_cvt_pk_bf16_f32 v83, v8, v9
	v_cvt_pk_bf16_f32 v84, v2, v3
	v_cvt_pk_bf16_f32 v85, v4, v5
	global_store_dwordx4 v[86:87], v[82:85], off offset:256
	s_nop 1
	v_mov_b32_e32 v82, v108
	s_nop 1
	v_permlane16_swap_b32_e32 v108, v82
	v_add_f32_e32 v84, v108, v82
	v_mov_b32_e32 v85, v84
	s_nop 1
	v_permlane32_swap_b32_e32 v84, v85
	v_lshl_add_u64 v[82:83], v[152:153], 2, s[8:9]
	s_and_saveexec_b64 s[2:3], vcc
	s_cbranch_execz .LBB0_1655
	v_add_f32_e32 v84, v84, v85
	global_store_dword v[82:83], v84, off

; #define LAS __attribute__((address_space(3)))
; #define PG8_BAR __builtin_amdgcn_s_barrier()
; #define EPI_ROWS(u) { const int _l = lane_id(); fr = _l & 15; fq = _l >> 4; } const int row0 = (u).pm * 256 + wr * 64 + fr
;     ...
;         if constexpr (ALIGN_EPI) { if (wr == 0) PG8_BAR; }
;     __device__ __forceinline__ void operator()(const f32x4 (&acc_)[2][2][4][2], const pg8::Unit& u, int wr, int wc, int fr, int fq) const {
;     ...
;         EPI_ROWS(u); const LAS float* rsl = (const LAS float*)(lds + EPI_RS + u.par * 1024) + wr * 64 + fr; const LAS float* cwl = (const LAS float*)(lds + EPI_CW + u.par * 4096) + wc * 32 + 8 * fq; bf16_t* act = (bf16_t*)(ws + WS_ACT); float* halo = (float*)(ws + WS_HALO) + (size_t)u.pm * 4 * DFF2;
;         const int ch = u.pn * 128 + wc * 32 + 8 * fq;
;         const bool prompt = u.pm < MP / 256;
;         LAS float* hl = (LAS float*)(lds + EPI_LDS);
; #pragma unroll
;         for (int ai = 0; ai < 2; ++ai)
; #pragma unroll
;             for (int m = 0; m < 4; ++m) {
;                 const int r = EPI_ROW(ai, m); const float rs = rsl[ai * 128 + m * 16];
; #pragma unroll
;                 for (int bj = 0; bj < 2; ++bj) { acc[ai][bj][m][0] = acc[ai][bj][m][0] * rs; acc[ai][bj][m][1] = acc[ai][bj][m][1] * rs; }
;                 float* so = nullptr;
;                 if (prompt) { const int t = r & (SEQ - 1); if (t >= SEQ - 2) so = out + O_CVP + (((size_t)layer * BATCH + (r >> 11)) * 2 + (t - (SEQ - 2))) * DFF2; }
;                 else { const int rr = r - MP, t = rr & (DECS - 1); if (t >= DECS - 2) so = out + O_CVS + (((size_t)layer * DECB + (rr >> 6)) * 2 + (t - (DECS - 2))) * DFF2; }
;                 if (so) {
; #pragma unroll
;                     for (int bj = 0; bj < 2; ++bj) { *(f32x4*)(so + bj * DFF + ch) = acc[ai][bj][m][0]; *(f32x4*)(so + bj * DFF + ch + 4) = acc[ai][bj][m][1]; } }
.LBB0_1786:
	s_lshl_b32 s2, s79, 10
	v_mbcnt_lo_u32_b32 v146, -1, 0
	v_mbcnt_hi_u32_b32 v146, -1, v146
	s_add_i32 s2, s82, s2
	v_and_b32_e32 v210, 15, v146
	s_mul_i32 s3, s8, 0x2c000
	v_lshl_add_u32 v133, v210, 2, s2
	s_mul_hi_i32 s2, s8, 0x2c000
	s_add_u32 s14, s65, s3
	s_addc_u32 s15, s16, s2
	s_lshl_b32 s2, s10, 7
	v_readlane_b32 s3, v255, 32
	ds_read_b32 v0, v133
	v_ashrrev_i32_e32 v137, 4, v146
	s_or_b32 s2, s2, s3
	v_lshlrev_b32_e32 v136, 3, v137
	s_cmp_lt_i32 s8, 64
	v_add_u32_e32 v194, s2, v136
	s_cselect_b64 s[12:13], -1, 0
	s_cmp_gt_i32 s8, 63
	s_cselect_b64 s[2:3], -1, 0
	v_ashrrev_i32_e32 v195, 31, v194
	v_cmp_gt_u32_e32 vcc, 2, v210
	s_and_b64 s[10:11], s[24:25], s[12:13]
	v_lshl_add_u64 v[130:131], v[194:195], 2, s[14:15]
	s_waitcnt lgkmcnt(0)
	v_pk_mul_f32 v[128:129], v[128:129], v[0:1] op_sel_hi:[1,0]
	v_pk_mul_f32 v[126:127], v[126:127], v[0:1] op_sel_hi:[1,0]
	v_pk_mul_f32 v[96:97], v[96:97], v[0:1] op_sel_hi:[1,0]
	v_pk_mul_f32 v[94:95], v[94:95], v[0:1] op_sel_hi:[1,0]
	v_pk_mul_f32 v[124:125], v[124:125], v[0:1] op_sel_hi:[1,0]
	v_pk_mul_f32 v[122:123], v[122:123], v[0:1] op_sel_hi:[1,0]
	v_pk_mul_f32 v[92:93], v[92:93], v[0:1] op_sel_hi:[1,0]
	v_pk_mul_f32 v[90:91], v[90:91], v[0:1] op_sel_hi:[1,0]
	s_and_b64 s[14:15], s[10:11], vcc
	s_cselect_b32 s100, 1, 0
	s_cmp_eq_u64 s[24:25], 0
	s_cbranch_scc1 .Lxb_up
	s_barrier
.Lxb_up:
	s_cmp_lg_u32 s100, 0
	s_and_saveexec_b64 s[10:11], s[14:15]
	s_cbranch_execz .LBB0_1788
	v_mul_u32_u24_e32 v0, 0xb000, v210
	v_lshl_add_u64 v[134:135], v[130:131], 0, v[0:1]
	global_store_dwordx4 v[134:135], v[126:129], off
	global_store_dwordx4 v[134:135], v[94:97], off offset:16
	v_add_co_u32_e32 v134, vcc, 0x5000, v134
	s_nop 1
	v_addc_co_u32_e32 v135, vcc, 0, v135, vcc
	global_store_dwordx4 v[134:135], v[122:125], off offset:2048
	global_store_dwordx4 v[134:135], v[90:93], off offset:2064

; __device__ __forceinline__ float bf_lo(unsigned w) { return __uint_as_float(w << 16); }
; __device__ __forceinline__ float bf_hi(unsigned w) { return __uint_as_float(w & 0xffff0000u); }
; __device__ __forceinline__ int lane_id() { int l; asm volatile("v_mbcnt_lo_u32_b32 %0, -1, 0\n\tv_mbcnt_hi_u32_b32 %0, -1, %0" : "=v"(l)); return l; }
; #define PG8_BAR __builtin_amdgcn_s_barrier()
;     ...
;         if constexpr (ALIGN_EPI) { if (wr == 0) PG8_BAR; }
;     __device__ __forceinline__ void operator()(const f32x4 (&acc)[2][2][NM][2], const pg8::Unit& u, int wr, int wc, int fr, int fq) const {
;         { const int _l = lane_id(); fr = _l & 15; fq = _l >> 4; } const int row0 = u.pm * (64 * NM) + wr * (16 * NM) + fr;
;         const int c0 = u.pn * 256 + wc * 32 + 8 * fq; bf16_t* XB = (bf16_t*)(ws + WS_XB); float* ssq = (float*)(ws + WS_SSQP) + (size_t)(nidx * 32 + u.pn * 4 + wc) * MT;
;         u32x4 q[2][NM][2];
;         if (!first) {
; #pragma unroll
;             for (int ai = 0; ai < 2; ++ai)
; #pragma unroll
;                 for (int m = 0; m < NM; ++m)
; #pragma unroll
;                     for (int bj = 0; bj < 2; ++bj) q[ai][m][bj] = *(const u32x4*)(XB + (size_t)(row0 + ai * (32 * NM) + m * 16) * DM + c0 + bj * 128);
;             asm volatile("" ::: "memory");
;         }
;         float sqv[2][NM];
; #pragma unroll
;         for (int ai = 0; ai < 2; ++ai)
; #pragma unroll
;             for (int m = 0; m < NM; ++m) {
;                 const int r = row0 + ai * (32 * NM) + m * 16; float sq = 0.f;
; #pragma unroll
;                 for (int bj = 0; bj < 2; ++bj) { const int c = c0 + bj * 128; f32x4 a, b;
;                     if (first) { const float* xo = (r < MP ? xp + (size_t)r * DM : xs + (size_t)(r - MP) * DM) + c; a = *(const f32x4*)xo; b = *(const f32x4*)(xo + 4); }
;                     else { const u32x4 w = q[ai][m][bj]; a = (f32x4){bf_lo(w.x), bf_hi(w.x), bf_lo(w.y), bf_hi(w.y)}; b = (f32x4){bf_lo(w.z), bf_hi(w.z), bf_lo(w.w), bf_hi(w.w)}; }
;                     a = a + acc[ai][bj][m][0]; b = b + acc[ai][bj][m][1];
;                     *(u32x4*)(XB + (size_t)r * DM + c) = pack8(a, b);
;                     sq += ((a[0] * a[0] + a[1] * a[1]) + (a[2] * a[2] + a[3] * a[3])) + ((b[0] * b[0] + b[1] * b[1]) + (b[2] * b[2] + b[3] * b[3])); }
.LBB0_2161:
	s_mul_i32 s2, s59, 0xc0
	s_add_i32 s2, s2, s39
	v_mbcnt_lo_u32_b32 v168, -1, 0
	v_mbcnt_hi_u32_b32 v168, -1, v168
	v_readlane_b32 s3, v255, 32
	v_and_or_b32 v152, v168, 15, s2
	s_lshl_b32 s2, s58, 8
	v_ashrrev_i32_e32 v90, 1, v168
	s_or_b32 s2, s2, s3
	v_and_b32_e32 v90, -8, v90
	v_add_u32_e32 v90, s2, v90
	v_ashrrev_i32_e32 v91, 31, v90
	v_lshlrev_b64 v[154:155], 1, v[90:91]
	v_ashrrev_i32_e32 v153, 31, v152
	v_lshl_add_u64 v[90:91], s[10:11], 0, v[154:155]
	v_lshlrev_b64 v[174:175], 12, v[152:153]
	v_lshl_add_u64 v[92:93], v[90:91], 0, v[174:175]
	global_load_dwordx4 v[170:173], v[92:93], off
	global_load_dwordx4 v[138:141], v[92:93], off offset:256
	s_lshl_b32 s2, s58, 2
	s_add_i32 s2, s2, s52
	s_mul_hi_i32 s3, s2, 0x12000
	s_mul_i32 s2, s2, 0x12000
	s_add_u32 s14, s50, s2
	s_addc_u32 s15, s51, s3
	s_mov_b64 s[2:3], 0x10000
	v_lshl_add_u64 v[164:165], v[174:175], 0, s[2:3]
	v_lshl_add_u64 v[92:93], v[90:91], 0, v[164:165]
	global_load_dwordx4 v[134:137], v[92:93], off
	global_load_dwordx4 v[130:133], v[92:93], off offset:256
	v_lshl_add_u64 v[162:163], v[174:175], 0, s[76:77]
	v_lshl_add_u64 v[92:93], v[90:91], 0, v[162:163]
	global_load_dwordx4 v[126:129], v[92:93], off
	global_load_dwordx4 v[122:125], v[92:93], off offset:256
	s_mov_b64 s[2:3], 0x60000
	v_lshl_add_u64 v[160:161], v[174:175], 0, s[2:3]
	v_lshl_add_u64 v[92:93], v[90:91], 0, v[160:161]
	global_load_dwordx4 v[118:121], v[92:93], off
	global_load_dwordx4 v[114:117], v[92:93], off offset:256
	s_mov_b64 s[2:3], 0x70000
	v_lshl_add_u64 v[158:159], v[174:175], 0, s[2:3]
	v_lshl_add_u64 v[92:93], v[90:91], 0, v[158:159]
	global_load_dwordx4 v[102:105], v[92:93], off
	global_load_dwordx4 v[98:101], v[92:93], off offset:256
	s_mov_b64 s[2:3], 0x80000
	v_lshl_add_u64 v[156:157], v[174:175], 0, s[2:3]
	v_lshl_add_u64 v[90:91], v[90:91], 0, v[156:157]
	global_load_dwordx4 v[94:97], v[90:91], off
	s_nop 0
	global_load_dwordx4 v[90:93], v[90:91], off offset:256
	v_lshl_add_u64 v[174:175], s[10:11], 0, v[174:175]
	v_cmp_gt_u32_e32 vcc, 16, v168
	s_waitcnt vmcnt(0)
	s_cselect_b32 s100, 1, 0
	s_cmp_eq_u64 s[8:9], 0
	s_cbranch_scc1 .Lxb_dn
	s_barrier
.Lxb_dn:
	s_cmp_lg_u32 s100, 0
	v_lshlrev_b32_e32 v176, 16, v170
	v_and_b32_e32 v177, 0xffff0000, v170
	v_lshlrev_b32_e32 v170, 16, v171
	v_and_b32_e32 v171, 0xffff0000, v171
	v_lshlrev_b32_e32 v178, 16, v172
	v_and_b32_e32 v179, 0xffff0000, v172
	v_lshlrev_b32_e32 v172, 16, v173
	v_and_b32_e32 v173, 0xffff0000, v173
	v_pk_add_f32 v[112:113], v[112:113], v[170:171]
	v_pk_add_f32 v[170:171], v[110:111], v[176:177]
	v_pk_add_f32 v[172:173], v[108:109], v[172:173]
	v_pk_add_f32 v[176:177], v[106:107], v[178:179]
	v_cvt_pk_bf16_f32 v108, v170, v171
	v_cvt_pk_bf16_f32 v109, v112, v113
	v_cvt_pk_bf16_f32 v110, v176, v177
	v_cvt_pk_bf16_f32 v111, v172, v173
	v_lshl_add_u64 v[106:107], v[174:175], 0, v[154:155]
	global_store_dwordx4 v[106:107], v[108:111], off
	s_nop 1
	v_mul_f32_e32 v108, v171, v171
	v_mul_f32_e32 v109, v113, v113
	v_fmac_f32_e32 v108, v170, v170
	v_fmac_f32_e32 v109, v112, v112
	v_add_f32_e32 v108, v108, v109
	v_mul_f32_e32 v109, v177, v177
	v_mul_f32_e32 v110, v173, v173
	v_fmac_f32_e32 v109, v176, v176
	v_fmac_f32_e32 v110, v172, v172
	v_add_f32_e32 v109, v109, v110
	v_add_f32_e32 v169, v108, v109
	v_lshlrev_b32_e32 v108, 16, v138
	v_and_b32_e32 v109, 0xffff0000, v138
	v_lshlrev_b32_e32 v110, 16, v139
	v_and_b32_e32 v111, 0xffff0000, v139
	v_lshlrev_b32_e32 v112, 16, v140
	v_and_b32_e32 v113, 0xffff0000, v140
	v_lshlrev_b32_e32 v138, 16, v141
	v_and_b32_e32 v139, 0xffff0000, v141
	v_pk_add_f32 v[88:89], v[88:89], v[110:111]
	v_pk_add_f32 v[86:87], v[86:87], v[108:109]
	v_pk_add_f32 v[108:109], v[84:85], v[138:139]
	v_pk_add_f32 v[110:111], v[82:83], v[112:113]
	v_cvt_pk_bf16_f32 v82, v86, v87
	v_cvt_pk_bf16_f32 v83, v88, v89
	v_cvt_pk_bf16_f32 v84, v110, v111
	v_cvt_pk_bf16_f32 v85, v108, v109
	global_store_dwordx4 v[106:107], v[82:85], off offset:256
	v_lshlrev_b32_e32 v106, 16, v137
	v_and_b32_e32 v107, 0xffff0000, v137
	v_mul_f32_e32 v82, v87, v87
	v_mul_f32_e32 v83, v89, v89
	v_fmac_f32_e32 v82, v86, v86
	v_fmac_f32_e32 v83, v88, v88
	v_add_f32_e32 v82, v82, v83
	v_mul_f32_e32 v83, v111, v111
	v_mul_f32_e32 v84, v109, v109
	v_fmac_f32_e32 v83, v110, v110
	v_fmac_f32_e32 v84, v108, v108
	v_add_f32_e32 v83, v83, v84
	v_add_f32_e32 v82, v82, v83
	v_add_f32_e32 v108, v169, v82
	v_lshlrev_b32_e32 v82, 16, v134
	v_and_b32_e32 v83, 0xffff0000, v134
	v_lshlrev_b32_e32 v84, 16, v135
	v_and_b32_e32 v85, 0xffff0000, v135
	v_lshlrev_b32_e32 v88, 16, v136
	v_and_b32_e32 v89, 0xffff0000, v136
	v_pk_add_f32 v[80:81], v[80:81], v[84:85]
	v_pk_add_f32 v[78:79], v[78:79], v[82:83]
	v_pk_add_f32 v[76:77], v[76:77], v[106:107]
	v_pk_add_f32 v[74:75], v[74:75], v[88:89]
	v_lshl_add_u64 v[86:87], s[10:11], 0, v[164:165]
	v_cvt_pk_bf16_f32 v82, v78, v79
	v_cvt_pk_bf16_f32 v83, v80, v81
	v_cvt_pk_bf16_f32 v84, v74, v75
	v_cvt_pk_bf16_f32 v85, v76, v77
	v_lshl_add_u64 v[86:87], v[86:87], 0, v[154:155]
	global_store_dwordx4 v[86:87], v[82:85], off
	v_lshlrev_b32_e32 v88, 16, v132
	v_and_b32_e32 v89, 0xffff0000, v132
	v_lshlrev_b32_e32 v82, 16, v130
	v_and_b32_e32 v83, 0xffff0000, v130
	v_lshlrev_b32_e32 v84, 16, v131
	v_and_b32_e32 v85, 0xffff0000, v131
	v_lshlrev_b32_e32 v106, 16, v133
	v_and_b32_e32 v107, 0xffff0000, v133
	v_pk_add_f32 v[72:73], v[72:73], v[84:85]
	v_pk_add_f32 v[70:71], v[70:71], v[82:83]
	v_pk_add_f32 v[68:69], v[68:69], v[106:107]
	v_pk_add_f32 v[66:67], v[66:67], v[88:89]
	v_cvt_pk_bf16_f32 v82, v70, v71
	v_cvt_pk_bf16_f32 v83, v72, v73
	v_cvt_pk_bf16_f32 v84, v66, v67
	v_cvt_pk_bf16_f32 v85, v68, v69
; __device__ __forceinline__ float bf_lo(unsigned w) { return __uint_as_float(w << 16); }
; __device__ __forceinline__ float bf_hi(unsigned w) { return __uint_as_float(w & 0xffff0000u); }
; __device__ __forceinline__ u32x4 pack8(const f32x4 a, const f32x4 b) { u32x4 w; w.x = cvt_pk_bf16(a[0], a[1]); w.y = cvt_pk_bf16(a[2], a[3]); w.z = cvt_pk_bf16(b[0], b[1]); w.w = cvt_pk_bf16(b[2], b[3]); return w; }
;     __device__ __forceinline__ void operator()(const f32x4 (&acc)[2][2][NM][2], const pg8::Unit& u, int wr, int wc, int fr, int fq) const {
;     ...
;                 const int r = row0 + ai * (32 * NM) + m * 16; float sq = 0.f;
; #pragma unroll
;                 for (int bj = 0; bj < 2; ++bj) { const int c = c0 + bj * 128; f32x4 a, b;
;                     if (first) { const float* xo = (r < MP ? xp + (size_t)r * DM : xs + (size_t)(r - MP) * DM) + c; a = *(const f32x4*)xo; b = *(const f32x4*)(xo + 4); }
;                     else { const u32x4 w = q[ai][m][bj]; a = (f32x4){bf_lo(w.x), bf_hi(w.x), bf_lo(w.y), bf_hi(w.y)}; b = (f32x4){bf_lo(w.z), bf_hi(w.z), bf_lo(w.w), bf_hi(w.w)}; }
;                     a = a + acc[ai][bj][m][0]; b = b + acc[ai][bj][m][1];
;                     *(u32x4*)(XB + (size_t)r * DM + c) = pack8(a, b);
;                     sq += ((a[0] * a[0] + a[1] * a[1]) + (a[2] * a[2] + a[3] * a[3])) + ((b[0] * b[0] + b[1] * b[1]) + (b[2] * b[2] + b[3] * b[3])); }
;                 sqv[ai][m] = sq;
;             }
; #pragma unroll
;         for (int ai = 0; ai < 2; ++ai)
; #pragma unroll
;             for (int m = 0; m < NM; ++m) { const float sq = row4_sum(sqv[ai][m]); if (fq == 0) ssq[row0 + ai * (32 * NM) + m * 16] = sq; }
	global_store_dwordx4 v[86:87], v[82:85], off offset:256
	v_lshlrev_b32_e32 v88, 16, v128
	v_and_b32_e32 v89, 0xffff0000, v128
	v_lshlrev_b32_e32 v82, 16, v126
	v_and_b32_e32 v83, 0xffff0000, v126
	v_lshlrev_b32_e32 v84, 16, v127
	v_and_b32_e32 v85, 0xffff0000, v127
	v_lshlrev_b32_e32 v106, 16, v129
	v_and_b32_e32 v107, 0xffff0000, v129
	v_pk_add_f32 v[64:65], v[64:65], v[84:85]
	v_pk_add_f32 v[62:63], v[62:63], v[82:83]
	v_pk_add_f32 v[60:61], v[60:61], v[106:107]
	v_pk_add_f32 v[58:59], v[58:59], v[88:89]
	v_lshl_add_u64 v[86:87], s[10:11], 0, v[162:163]
	v_cvt_pk_bf16_f32 v82, v62, v63
	v_cvt_pk_bf16_f32 v83, v64, v65
	v_cvt_pk_bf16_f32 v84, v58, v59
	v_cvt_pk_bf16_f32 v85, v60, v61
	v_lshl_add_u64 v[86:87], v[86:87], 0, v[154:155]
	global_store_dwordx4 v[86:87], v[82:85], off
	v_lshlrev_b32_e32 v88, 16, v124
	v_and_b32_e32 v89, 0xffff0000, v124
	v_lshlrev_b32_e32 v82, 16, v122
	v_and_b32_e32 v83, 0xffff0000, v122
	v_lshlrev_b32_e32 v84, 16, v123
	v_and_b32_e32 v85, 0xffff0000, v123
	v_lshlrev_b32_e32 v106, 16, v125
	v_and_b32_e32 v107, 0xffff0000, v125
	v_pk_add_f32 v[56:57], v[56:57], v[84:85]
	v_pk_add_f32 v[54:55], v[54:55], v[82:83]
	v_pk_add_f32 v[52:53], v[52:53], v[106:107]
	v_pk_add_f32 v[50:51], v[50:51], v[88:89]
	v_cvt_pk_bf16_f32 v82, v54, v55
	v_cvt_pk_bf16_f32 v83, v56, v57
	v_cvt_pk_bf16_f32 v84, v50, v51
	v_cvt_pk_bf16_f32 v85, v52, v53
	global_store_dwordx4 v[86:87], v[82:85], off offset:256
	v_lshlrev_b32_e32 v88, 16, v120
	v_and_b32_e32 v89, 0xffff0000, v120
	v_lshlrev_b32_e32 v82, 16, v118
	v_and_b32_e32 v83, 0xffff0000, v118
	v_lshlrev_b32_e32 v84, 16, v119
	v_and_b32_e32 v85, 0xffff0000, v119
	v_lshlrev_b32_e32 v106, 16, v121
	v_and_b32_e32 v107, 0xffff0000, v121
	v_pk_add_f32 v[48:49], v[48:49], v[84:85]
	v_pk_add_f32 v[46:47], v[46:47], v[82:83]
	v_pk_add_f32 v[44:45], v[44:45], v[106:107]
	v_pk_add_f32 v[42:43], v[42:43], v[88:89]
	v_lshl_add_u64 v[86:87], s[10:11], 0, v[160:161]
	v_cvt_pk_bf16_f32 v82, v46, v47
	v_cvt_pk_bf16_f32 v83, v48, v49
	v_cvt_pk_bf16_f32 v84, v42, v43
	v_cvt_pk_bf16_f32 v85, v44, v45
	v_lshl_add_u64 v[86:87], v[86:87], 0, v[154:155]
	global_store_dwordx4 v[86:87], v[82:85], off
	v_lshlrev_b32_e32 v88, 16, v116
	v_and_b32_e32 v89, 0xffff0000, v116
	v_lshlrev_b32_e32 v82, 16, v114
	v_and_b32_e32 v83, 0xffff0000, v114
	v_lshlrev_b32_e32 v84, 16, v115
	v_and_b32_e32 v85, 0xffff0000, v115
	v_lshlrev_b32_e32 v106, 16, v117
	v_and_b32_e32 v107, 0xffff0000, v117
	v_pk_add_f32 v[40:41], v[40:41], v[84:85]
	v_pk_add_f32 v[38:39], v[38:39], v[82:83]
	v_pk_add_f32 v[36:37], v[36:37], v[106:107]
	v_pk_add_f32 v[34:35], v[34:35], v[88:89]
	v_cvt_pk_bf16_f32 v82, v38, v39
	v_cvt_pk_bf16_f32 v83, v40, v41
	v_cvt_pk_bf16_f32 v84, v34, v35
	v_cvt_pk_bf16_f32 v85, v36, v37
	global_store_dwordx4 v[86:87], v[82:85], off offset:256
	v_lshlrev_b32_e32 v88, 16, v104
	v_and_b32_e32 v89, 0xffff0000, v104
	v_lshlrev_b32_e32 v82, 16, v102
	v_and_b32_e32 v83, 0xffff0000, v102
	v_lshlrev_b32_e32 v84, 16, v103
	v_and_b32_e32 v85, 0xffff0000, v103
	v_lshlrev_b32_e32 v102, 16, v105
	v_and_b32_e32 v103, 0xffff0000, v105
	v_pk_add_f32 v[32:33], v[32:33], v[84:85]
	v_pk_add_f32 v[30:31], v[30:31], v[82:83]
	v_pk_add_f32 v[28:29], v[28:29], v[102:103]
	v_pk_add_f32 v[26:27], v[26:27], v[88:89]
	v_lshl_add_u64 v[86:87], s[10:11], 0, v[158:159]
	v_cvt_pk_bf16_f32 v82, v30, v31
	v_cvt_pk_bf16_f32 v83, v32, v33
	v_cvt_pk_bf16_f32 v84, v26, v27
	v_cvt_pk_bf16_f32 v85, v28, v29
	v_lshl_add_u64 v[86:87], v[86:87], 0, v[154:155]
	global_store_dwordx4 v[86:87], v[82:85], off
	v_lshlrev_b32_e32 v88, 16, v100
	v_and_b32_e32 v89, 0xffff0000, v100
	v_lshlrev_b32_e32 v82, 16, v98
	v_and_b32_e32 v83, 0xffff0000, v98
	v_lshlrev_b32_e32 v84, 16, v99
	v_and_b32_e32 v85, 0xffff0000, v99
	v_lshlrev_b32_e32 v98, 16, v101
	v_and_b32_e32 v99, 0xffff0000, v101
	v_pk_add_f32 v[24:25], v[24:25], v[84:85]
	v_pk_add_f32 v[22:23], v[22:23], v[82:83]
	v_pk_add_f32 v[20:21], v[20:21], v[98:99]
	v_pk_add_f32 v[18:19], v[18:19], v[88:89]
	v_cvt_pk_bf16_f32 v82, v22, v23
	v_cvt_pk_bf16_f32 v83, v24, v25
	v_cvt_pk_bf16_f32 v84, v18, v19
	v_cvt_pk_bf16_f32 v85, v20, v21
	global_store_dwordx4 v[86:87], v[82:85], off offset:256
	v_lshlrev_b32_e32 v88, 16, v96
	v_and_b32_e32 v89, 0xffff0000, v96
	v_lshlrev_b32_e32 v82, 16, v94
	v_and_b32_e32 v83, 0xffff0000, v94
	v_lshlrev_b32_e32 v84, 16, v95
	v_and_b32_e32 v85, 0xffff0000, v95
	v_lshlrev_b32_e32 v94, 16, v97
	v_and_b32_e32 v95, 0xffff0000, v97
	v_pk_add_f32 v[16:17], v[16:17], v[84:85]
	v_pk_add_f32 v[14:15], v[14:15], v[82:83]
	v_lshl_add_u64 v[86:87], s[10:11], 0, v[156:157]
	v_pk_add_f32 v[12:13], v[12:13], v[94:95]
	v_pk_add_f32 v[10:11], v[10:11], v[88:89]
	v_cvt_pk_bf16_f32 v82, v14, v15
	v_cvt_pk_bf16_f32 v83, v16, v17
	v_cvt_pk_bf16_f32 v84, v10, v11
	v_cvt_pk_bf16_f32 v85, v12, v13
	v_lshl_add_u64 v[86:87], v[86:87], 0, v[154:155]
	global_store_dwordx4 v[86:87], v[82:85], off
	v_lshlrev_b32_e32 v88, 16, v92
	v_and_b32_e32 v89, 0xffff0000, v92
	v_lshlrev_b32_e32 v82, 16, v90
	v_and_b32_e32 v83, 0xffff0000, v90
	v_lshlrev_b32_e32 v84, 16, v91
	v_and_b32_e32 v85, 0xffff0000, v91
	v_lshlrev_b32_e32 v90, 16, v93
	v_and_b32_e32 v91, 0xffff0000, v93
	v_pk_add_f32 v[6:7], v[6:7], v[82:83]
	v_pk_add_f32 v[8:9], v[8:9], v[84:85]
	v_pk_add_f32 v[4:5], v[4:5], v[90:91]
	v_pk_add_f32 v[2:3], v[2:3], v[88:89]
	v_cvt_pk_bf16_f32 v82, v6, v7
	v_cvt_pk_bf16_f32 v83, v8, v9
	v_cvt_pk_bf16_f32 v84, v2, v3
	v_cvt_pk_bf16_f32 v85, v4, v5
	global_store_dwordx4 v[86:87], v[82:85], off offset:256
	s_nop 1
	v_mov_b32_e32 v82, v108
	s_nop 1
	v_permlane16_swap_b32_e32 v108, v82
	v_add_f32_e32 v84, v108, v82
	v_mov_b32_e32 v85, v84
	s_nop 1
	v_permlane32_swap_b32_e32 v84, v85
	v_lshl_add_u64 v[82:83], v[152:153], 2, s[14:15]
	s_and_saveexec_b64 s[2:3], vcc
	s_cbranch_execz .LBB0_2163
	v_add_f32_e32 v84, v84, v85
	global_store_dword v[82:83], v84, off
